# NSA selected branch fast path: wave priority raised for the woven MFMA/exp2 compute segment, dropped before the end-of-iteration barrier
# speedup vs baseline: 1.0045x; 1.0041x over previous
; DI void nsa_item(const Params& p, int bk, int qb, char* smem, float Mb) {
;     ...
;                 for (int k4 = 0; k4 < 4; ++k4) {
;                     kf[k4][0] = *(const bf16x8*)(kb_ + k4 * 16 * 144); kf[k4][1] = *(const bf16x8*)(kb_ + k4 * 16 * 144 + 64);
;                     vf[k4][0] = *(const bf16x8*)(kb_ + 9216 + k4 * 16 * 144); vf[k4][1] = *(const bf16x8*)(kb_ + 9216 + k4 * 16 * 144 + 64);
;                 }
;                 const bool mine = (sub >> fr) & 1u;
;                 const float Ml = mine ? Mb : 3.0e38f;
;                 const bool diag = (j == cur);
; #pragma unroll
;                 for (int g = 0; g < 3; ++g) {
;                     f32x4 st[4];
;                     st_from(kf, qf[g], st, -Ml);
;                     if (diag) {
; #pragma unroll
;                         for (int k4 = 0; k4 < 4; ++k4)
; #pragma unroll
;                             for (int ii = 0; ii < 4; ++ii) {
;                                 const float pv = (j * 64 + k4 * 16 + fq * 4 + ii <= tq) ? __builtin_amdgcn_exp2f(st[k4][ii]) : 0.f;
;                                 st[k4][ii] = pv; ls[g] += pv;
;                             }
;                     } else {
; #pragma unroll
;                         for (int k4 = 0; k4 < 4; ++k4)
; #pragma unroll
;                             for (int ii = 0; ii < 4; ++ii) { const float pv = __builtin_amdgcn_exp2f(st[k4][ii]); st[k4][ii] = pv; ls[g] += pv; }
;                     }
;                     pv_from(vf, st, o[g]);
.Lsel_fast:
	s_setprio 1
	ds_read_b128 v[140:143], v116 offset:6976
	ds_read_b128 v[108:111], v116 offset:9216
	ds_read_b128 v[88:91], v116 offset:9280
	ds_read_b128 v[92:95], v116 offset:11520
	ds_read_b128 v[96:99], v116 offset:11584
	ds_read_b128 v[100:103], v116 offset:13824
	ds_read_b128 v[104:107], v116 offset:13888
	ds_read_b128 v[112:115], v116 offset:16128
	s_waitcnt lgkmcnt(7)
	ds_read_b128 v[116:119], v116 offset:16192
	v_mfma_f32_16x16x32_bf16 v[156:159], v[120:123], v[0:3], v[124:127]
	v_mfma_f32_16x16x32_bf16 v[164:167], v[132:135], v[0:3], v[124:127]
	v_mfma_f32_16x16x32_bf16 v[172:175], v[144:147], v[0:3], v[124:127]
	v_mfma_f32_16x16x32_bf16 v[180:183], v[152:155], v[0:3], v[124:127]
	v_mfma_f32_16x16x32_bf16 v[156:159], v[128:131], v[4:7], v[156:159]
	v_mfma_f32_16x16x32_bf16 v[164:167], v[136:139], v[4:7], v[164:167]
	v_mfma_f32_16x16x32_bf16 v[172:175], v[148:151], v[4:7], v[172:175]
	v_mfma_f32_16x16x32_bf16 v[180:183], v[140:143], v[4:7], v[180:183]
	v_mfma_f32_16x16x32_bf16 v[184:187], v[120:123], v[8:11], v[124:127]
	v_mfma_f32_16x16x32_bf16 v[176:179], v[132:135], v[8:11], v[124:127]
	v_mfma_f32_16x16x32_bf16 v[168:171], v[144:147], v[8:11], v[124:127]
	v_mfma_f32_16x16x32_bf16 v[160:163], v[152:155], v[8:11], v[124:127]
	s_nop 1
	v_mfma_f32_16x16x32_bf16 v[184:187], v[128:131], v[12:15], v[184:187]
	v_exp_f32_e32 v156, v156
	v_exp_f32_e32 v157, v157
	v_exp_f32_e32 v158, v158
	v_exp_f32_e32 v159, v159
	v_mfma_f32_16x16x32_bf16 v[176:179], v[136:139], v[12:15], v[176:179]
	v_exp_f32_e32 v164, v164
	v_exp_f32_e32 v165, v165
	v_exp_f32_e32 v166, v166
	v_exp_f32_e32 v167, v167
	v_mfma_f32_16x16x32_bf16 v[168:171], v[148:151], v[12:15], v[168:171]
	v_exp_f32_e32 v172, v172
	v_exp_f32_e32 v173, v173
	v_exp_f32_e32 v174, v174
	v_exp_f32_e32 v175, v175
	v_mfma_f32_16x16x32_bf16 v[160:163], v[140:143], v[12:15], v[160:163]
	v_exp_f32_e32 v180, v180
	v_exp_f32_e32 v181, v181
	v_exp_f32_e32 v182, v182
	v_exp_f32_e32 v183, v183
	v_pk_add_f32 v[254:255], v[156:157], v[158:159]
	v_pk_add_f32 v[254:255], v[254:255], v[164:165]
	v_pk_add_f32 v[254:255], v[254:255], v[166:167]
	v_cvt_pk_bf16_f32 v156, v156, v157
	v_cvt_pk_bf16_f32 v157, v158, v159
	v_cvt_pk_bf16_f32 v158, v164, v165
	v_cvt_pk_bf16_f32 v159, v166, v167
	v_pk_add_f32 v[164:165], v[172:173], v[174:175]
	v_pk_add_f32 v[164:165], v[164:165], v[180:181]
	v_pk_add_f32 v[164:165], v[164:165], v[182:183]
	v_cvt_pk_bf16_f32 v172, v172, v173
	v_cvt_pk_bf16_f32 v173, v174, v175
	v_cvt_pk_bf16_f32 v174, v180, v181
	v_cvt_pk_bf16_f32 v175, v182, v183
	v_pk_add_f32 v[254:255], v[254:255], v[164:165]
	v_add_f32_e32 v244, v244, v254
	v_add_f32_e32 v244, v244, v255
	s_waitcnt lgkmcnt(0)
; DI void nsa_item(const Params& p, int bk, int qb, char* smem, float Mb) {
;     ...
;                 for (int g = 0; g < 3; ++g) {
;                     f32x4 st[4];
;                     st_from(kf, qf[g], st, -Ml);
;                     if (diag) {
; #pragma unroll
;                         for (int k4 = 0; k4 < 4; ++k4)
; #pragma unroll
;                             for (int ii = 0; ii < 4; ++ii) {
;                                 const float pv = (j * 64 + k4 * 16 + fq * 4 + ii <= tq) ? __builtin_amdgcn_exp2f(st[k4][ii]) : 0.f;
;                                 st[k4][ii] = pv; ls[g] += pv;
;                             }
;                     } else {
; #pragma unroll
;                         for (int k4 = 0; k4 < 4; ++k4)
; #pragma unroll
;                             for (int ii = 0; ii < 4; ++ii) { const float pv = __builtin_amdgcn_exp2f(st[k4][ii]); st[k4][ii] = pv; ls[g] += pv; }
;                     }
;                     pv_from(vf, st, o[g]);
;                 }
;             }
;             lstore(bsel ^ 1);
;             __syncthreads();
;             bsel ^= 1; j = jn; m = mn;
	s_nop 1
	v_mfma_f32_16x16x32_bf16 v[68:71], v[108:111], v[156:159], v[68:71]
	v_exp_f32_e32 v184, v184
	v_mfma_f32_16x16x32_bf16 v[64:67], v[92:95], v[156:159], v[64:67]
	v_exp_f32_e32 v185, v185
	v_mfma_f32_16x16x32_bf16 v[60:63], v[100:103], v[156:159], v[60:63]
	v_exp_f32_e32 v186, v186
	v_mfma_f32_16x16x32_bf16 v[56:59], v[112:115], v[156:159], v[56:59]
	v_exp_f32_e32 v187, v187
	v_mfma_f32_16x16x32_bf16 v[68:71], v[88:91], v[172:175], v[68:71]
	v_exp_f32_e32 v176, v176
	v_mfma_f32_16x16x32_bf16 v[64:67], v[96:99], v[172:175], v[64:67]
	v_exp_f32_e32 v177, v177
	v_mfma_f32_16x16x32_bf16 v[60:63], v[104:107], v[172:175], v[60:63]
	v_exp_f32_e32 v178, v178
	v_mfma_f32_16x16x32_bf16 v[56:59], v[116:119], v[172:175], v[56:59]
	v_exp_f32_e32 v179, v179
	v_mfma_f32_16x16x32_bf16 v[156:159], v[120:123], v[16:19], v[124:127]
	v_exp_f32_e32 v168, v168
	v_mfma_f32_16x16x32_bf16 v[164:167], v[132:135], v[16:19], v[124:127]
	v_exp_f32_e32 v169, v169
	v_mfma_f32_16x16x32_bf16 v[172:175], v[144:147], v[16:19], v[124:127]
	v_exp_f32_e32 v170, v170
	v_mfma_f32_16x16x32_bf16 v[180:183], v[152:155], v[16:19], v[124:127]
	v_exp_f32_e32 v171, v171
	v_mfma_f32_16x16x32_bf16 v[156:159], v[128:131], v[20:23], v[156:159]
	v_exp_f32_e32 v160, v160
	v_mfma_f32_16x16x32_bf16 v[164:167], v[136:139], v[20:23], v[164:167]
	v_exp_f32_e32 v161, v161
	v_mfma_f32_16x16x32_bf16 v[172:175], v[148:151], v[20:23], v[172:175]
	v_exp_f32_e32 v162, v162
	v_mfma_f32_16x16x32_bf16 v[180:183], v[140:143], v[20:23], v[180:183]
	v_exp_f32_e32 v163, v163
	v_pk_add_f32 v[254:255], v[184:185], v[186:187]
	v_pk_add_f32 v[254:255], v[254:255], v[176:177]
	v_pk_add_f32 v[254:255], v[254:255], v[178:179]
	v_cvt_pk_bf16_f32 v184, v184, v185
	v_cvt_pk_bf16_f32 v185, v186, v187
	v_cvt_pk_bf16_f32 v186, v176, v177
	v_cvt_pk_bf16_f32 v187, v178, v179
	v_pk_add_f32 v[176:177], v[168:169], v[170:171]
	v_pk_add_f32 v[176:177], v[176:177], v[160:161]
	v_pk_add_f32 v[176:177], v[176:177], v[162:163]
	v_cvt_pk_bf16_f32 v168, v168, v169
	v_cvt_pk_bf16_f32 v169, v170, v171
	v_cvt_pk_bf16_f32 v170, v160, v161
	v_cvt_pk_bf16_f32 v171, v162, v163
	v_pk_add_f32 v[254:255], v[254:255], v[176:177]
	v_add_f32_e32 v243, v243, v254
	v_add_f32_e32 v243, v243, v255
	s_nop 1
	v_mfma_f32_16x16x32_bf16 v[52:55], v[108:111], v[184:187], v[52:55]
	v_exp_f32_e32 v156, v156
	v_exp_f32_e32 v157, v157
	v_mfma_f32_16x16x32_bf16 v[48:51], v[92:95], v[184:187], v[48:51]
	v_exp_f32_e32 v158, v158
	v_exp_f32_e32 v159, v159
	v_mfma_f32_16x16x32_bf16 v[44:47], v[100:103], v[184:187], v[44:47]
	v_exp_f32_e32 v164, v164
	v_exp_f32_e32 v165, v165
	v_mfma_f32_16x16x32_bf16 v[40:43], v[112:115], v[184:187], v[40:43]
	v_exp_f32_e32 v166, v166
	v_exp_f32_e32 v167, v167
	v_mfma_f32_16x16x32_bf16 v[52:55], v[88:91], v[168:171], v[52:55]
	v_exp_f32_e32 v172, v172
	v_exp_f32_e32 v173, v173
	v_mfma_f32_16x16x32_bf16 v[48:51], v[96:99], v[168:171], v[48:51]
	v_exp_f32_e32 v174, v174
	v_exp_f32_e32 v175, v175
	v_mfma_f32_16x16x32_bf16 v[44:47], v[104:107], v[168:171], v[44:47]
	v_exp_f32_e32 v180, v180
	v_exp_f32_e32 v181, v181
	v_mfma_f32_16x16x32_bf16 v[40:43], v[116:119], v[168:171], v[40:43]
	v_exp_f32_e32 v182, v182
	v_exp_f32_e32 v183, v183
	v_pk_add_f32 v[254:255], v[156:157], v[158:159]
	v_pk_add_f32 v[254:255], v[254:255], v[164:165]
	v_pk_add_f32 v[254:255], v[254:255], v[166:167]
	v_cvt_pk_bf16_f32 v156, v156, v157
	v_cvt_pk_bf16_f32 v157, v158, v159
	v_cvt_pk_bf16_f32 v158, v164, v165
	v_cvt_pk_bf16_f32 v159, v166, v167
	v_pk_add_f32 v[164:165], v[172:173], v[174:175]
	v_pk_add_f32 v[164:165], v[164:165], v[180:181]
	v_pk_add_f32 v[164:165], v[164:165], v[182:183]
	v_cvt_pk_bf16_f32 v172, v172, v173
	v_cvt_pk_bf16_f32 v173, v174, v175
	v_cvt_pk_bf16_f32 v174, v180, v181
	v_cvt_pk_bf16_f32 v175, v182, v183
	v_pk_add_f32 v[254:255], v[254:255], v[164:165]
	v_add_f32_e32 v241, v241, v254
	v_add_f32_e32 v241, v241, v255
	s_or_b64 exec, exec, s[12:13]
	s_and_b64 s[4:5], exec, s[4:5]
	s_or_b64 s[10:11], s[4:5], s[10:11]
	s_xor_b32 s22, s22, 1
	s_mul_i32 s4, s22, 0x4800
	v_add_u32_e32 v254, s4, v195
	s_waitcnt vmcnt(3)
	ds_write_b128 v254, v[72:75]
	v_mfma_f32_16x16x32_bf16 v[36:39], v[108:111], v[156:159], v[36:39]
	v_mfma_f32_16x16x32_bf16 v[32:35], v[92:95], v[156:159], v[32:35]
	s_waitcnt vmcnt(2)
	ds_write_b128 v254, v[76:79] offset:4608
	v_mfma_f32_16x16x32_bf16 v[28:31], v[100:103], v[156:159], v[28:31]
	v_mfma_f32_16x16x32_bf16 v[24:27], v[112:115], v[156:159], v[24:27]
	s_waitcnt vmcnt(1)
	ds_write_b128 v254, v[80:83] offset:9216
	v_mfma_f32_16x16x32_bf16 v[36:39], v[88:91], v[172:175], v[36:39]
	v_mfma_f32_16x16x32_bf16 v[32:35], v[96:99], v[172:175], v[32:35]
	s_waitcnt vmcnt(0)
	ds_write_b128 v254, v[84:87] offset:13824
	v_mfma_f32_16x16x32_bf16 v[28:31], v[104:107], v[172:175], v[28:31]
	v_mfma_f32_16x16x32_bf16 v[24:27], v[116:119], v[172:175], v[24:27]
	s_setprio 0
	s_branch .Lsel_bot2
